# RMSNorm loops (N2 and final norm): sample-row split-K partials, second batch of four loaded into the idle row registers together with the first (one wait) when rows 1..3 of the trip are invalid
# baseline (speedup 1.0000x reference)
;     ...
;         for (int b = 0; b < 4; ++b) { const int r = r0 + b * nw;
;             if (r < TT) {
;                 float ss = 0.f;
; #pragma unroll
;                 for (int i = 0; i < 4; ++i) {
;                     if (nsl && r >= TP) {
;                         const float* s = scr + (size_t)(r - TP) * DM + i * 256 + lane * 4;
;                         for (int q = 0; q < nsl; ++q) v[b][i] = v[b][i] + *(const f32x4*)(s + (size_t)q * TS * DM);
;                         if (!final_inplace) *(f32x4*)(X + (size_t)r * DM + i * 256 + lane * 4) = v[b][i]; }
;                     ss += v[b][i][0] * v[b][i][0] + v[b][i][1] * v[b][i][1] + v[b][i][2] * v[b][i][2] + v[b][i][3] * v[b][i][3]; }
.LBB0_706:
	s_or_b64 exec, exec, s[4:5]
	v_add_u32_e32 v16, 0xffffc000, v102
	v_lshlrev_b64 v[100:101], 12, v[16:17]
	v_cmp_lt_i32_e64 s[46:47], s15, v102
	v_lshl_add_u64 v[100:101], v[82:83], 0, v[100:101]
	s_and_saveexec_b64 s[4:5], s[46:47]
	s_cbranch_execz .LBB0_711
	global_load_dwordx4 v[120:123], v[100:101], off
	global_load_dwordx4 v[124:127], v[100:101], off offset:1024
	global_load_dwordx4 v[128:131], v[100:101], off offset:2048
	global_load_dwordx4 v[132:135], v[100:101], off offset:3072
	v_add_co_u32_e32 v136, vcc, 0x200000, v100
	s_nop 1
	v_addc_co_u32_e32 v137, vcc, 0, v101, vcc
	global_load_dwordx4 v[140:143], v[136:137], off
	global_load_dwordx4 v[144:147], v[136:137], off offset:1024
	global_load_dwordx4 v[148:151], v[136:137], off offset:2048
	global_load_dwordx4 v[152:155], v[136:137], off offset:3072
	v_add_co_u32_e32 v188, vcc, 0x400000, v100
	s_nop 1
	v_addc_co_u32_e32 v189, vcc, 0, v101, vcc
	global_load_dwordx4 v[156:159], v[188:189], off
	global_load_dwordx4 v[160:163], v[188:189], off offset:1024
	global_load_dwordx4 v[164:167], v[188:189], off offset:2048
	global_load_dwordx4 v[168:171], v[188:189], off offset:3072
	v_add_co_u32_e32 v190, vcc, 0x600000, v100
	s_nop 1
	v_addc_co_u32_e32 v191, vcc, 0, v101, vcc
	global_load_dwordx4 v[172:175], v[190:191], off
	global_load_dwordx4 v[176:179], v[190:191], off offset:1024
	global_load_dwordx4 v[180:183], v[190:191], off offset:2048
	global_load_dwordx4 v[184:187], v[190:191], off offset:3072
	s_or_b64 s[6:7], s[44:45], s[42:43]
	s_or_b64 s[6:7], s[6:7], s[40:41]
	s_cmp_eq_u64 s[6:7], 0
	s_cbranch_scc0 .Lpb_slow_b
	v_add_co_u32_e32 v192, vcc, 0x800000, v100
	s_nop 1
	v_addc_co_u32_e32 v193, vcc, 0, v101, vcc
	global_load_dwordx4 v[18:21], v[192:193], off
	global_load_dwordx4 v[22:25], v[192:193], off offset:1024
	global_load_dwordx4 v[26:29], v[192:193], off offset:2048
	global_load_dwordx4 v[30:33], v[192:193], off offset:3072
	v_add_co_u32_e32 v136, vcc, 0xa00000, v100
	s_nop 1
	v_addc_co_u32_e32 v137, vcc, 0, v101, vcc
	global_load_dwordx4 v[34:37], v[136:137], off
	global_load_dwordx4 v[38:41], v[136:137], off offset:1024
	global_load_dwordx4 v[42:45], v[136:137], off offset:2048
	global_load_dwordx4 v[46:49], v[136:137], off offset:3072
	v_add_co_u32_e32 v188, vcc, 0xc00000, v100
	s_nop 1
	v_addc_co_u32_e32 v189, vcc, 0, v101, vcc
	global_load_dwordx4 v[50:53], v[188:189], off
	global_load_dwordx4 v[54:57], v[188:189], off offset:1024
	global_load_dwordx4 v[58:61], v[188:189], off offset:2048
	global_load_dwordx4 v[62:65], v[188:189], off offset:3072
	v_add_co_u32_e32 v190, vcc, 0xe00000, v100
	s_nop 1
	v_addc_co_u32_e32 v191, vcc, 0, v101, vcc
	global_load_dwordx4 v[230:233], v[190:191], off
	global_load_dwordx4 v[234:237], v[190:191], off offset:1024
	global_load_dwordx4 v[238:241], v[190:191], off offset:2048
	global_load_dwordx4 v[242:245], v[190:191], off offset:3072
	s_waitcnt vmcnt(0)
	v_pk_add_f32 v[78:79], v[78:79], v[120:121]
	v_pk_add_f32 v[80:81], v[80:81], v[122:123]
	v_pk_add_f32 v[78:79], v[78:79], v[140:141]
	v_pk_add_f32 v[80:81], v[80:81], v[142:143]
	v_pk_add_f32 v[78:79], v[78:79], v[156:157]
	v_pk_add_f32 v[80:81], v[80:81], v[158:159]
	v_pk_add_f32 v[78:79], v[78:79], v[172:173]
	v_pk_add_f32 v[80:81], v[80:81], v[174:175]
	v_pk_add_f32 v[74:75], v[74:75], v[124:125]
	v_pk_add_f32 v[76:77], v[76:77], v[126:127]
	v_pk_add_f32 v[74:75], v[74:75], v[144:145]
	v_pk_add_f32 v[76:77], v[76:77], v[146:147]
	v_pk_add_f32 v[74:75], v[74:75], v[160:161]
	v_pk_add_f32 v[76:77], v[76:77], v[162:163]
	v_pk_add_f32 v[74:75], v[74:75], v[176:177]
	v_pk_add_f32 v[76:77], v[76:77], v[178:179]
	v_pk_add_f32 v[70:71], v[70:71], v[128:129]
	v_pk_add_f32 v[72:73], v[72:73], v[130:131]
	v_pk_add_f32 v[70:71], v[70:71], v[148:149]
	v_pk_add_f32 v[72:73], v[72:73], v[150:151]
	v_pk_add_f32 v[70:71], v[70:71], v[164:165]
	v_pk_add_f32 v[72:73], v[72:73], v[166:167]
	v_pk_add_f32 v[70:71], v[70:71], v[180:181]
	v_pk_add_f32 v[72:73], v[72:73], v[182:183]
	v_pk_add_f32 v[66:67], v[66:67], v[132:133]
	v_pk_add_f32 v[68:69], v[68:69], v[134:135]
	v_pk_add_f32 v[66:67], v[66:67], v[152:153]
	v_pk_add_f32 v[68:69], v[68:69], v[154:155]
	v_pk_add_f32 v[66:67], v[66:67], v[168:169]
	v_pk_add_f32 v[68:69], v[68:69], v[170:171]
	v_pk_add_f32 v[66:67], v[66:67], v[184:185]
	v_pk_add_f32 v[68:69], v[68:69], v[186:187]
	v_pk_add_f32 v[78:79], v[78:79], v[18:19]
	v_pk_add_f32 v[80:81], v[80:81], v[20:21]
	v_pk_add_f32 v[78:79], v[78:79], v[34:35]
	v_pk_add_f32 v[80:81], v[80:81], v[36:37]
	v_pk_add_f32 v[78:79], v[78:79], v[50:51]
	v_pk_add_f32 v[80:81], v[80:81], v[52:53]
	v_pk_add_f32 v[78:79], v[78:79], v[230:231]
	v_pk_add_f32 v[80:81], v[80:81], v[232:233]
	v_pk_add_f32 v[74:75], v[74:75], v[22:23]
	v_pk_add_f32 v[76:77], v[76:77], v[24:25]
	v_pk_add_f32 v[74:75], v[74:75], v[38:39]
	v_pk_add_f32 v[76:77], v[76:77], v[40:41]
	v_pk_add_f32 v[74:75], v[74:75], v[54:55]
	v_pk_add_f32 v[76:77], v[76:77], v[56:57]
	v_pk_add_f32 v[74:75], v[74:75], v[234:235]
	v_pk_add_f32 v[76:77], v[76:77], v[236:237]
	v_pk_add_f32 v[70:71], v[70:71], v[26:27]
	v_pk_add_f32 v[72:73], v[72:73], v[28:29]
	v_pk_add_f32 v[70:71], v[70:71], v[42:43]
	v_pk_add_f32 v[72:73], v[72:73], v[44:45]
	v_pk_add_f32 v[70:71], v[70:71], v[58:59]
	v_pk_add_f32 v[72:73], v[72:73], v[60:61]
	v_pk_add_f32 v[70:71], v[70:71], v[238:239]
	v_pk_add_f32 v[72:73], v[72:73], v[240:241]
	v_pk_add_f32 v[66:67], v[66:67], v[30:31]
	v_pk_add_f32 v[68:69], v[68:69], v[32:33]
	v_pk_add_f32 v[66:67], v[66:67], v[46:47]
	v_pk_add_f32 v[68:69], v[68:69], v[48:49]
	v_pk_add_f32 v[66:67], v[66:67], v[62:63]
	v_pk_add_f32 v[68:69], v[68:69], v[64:65]
	v_pk_add_f32 v[66:67], v[66:67], v[242:243]
	v_pk_add_f32 v[68:69], v[68:69], v[244:245]
	s_branch .Lpb_store_b
; __device__ __forceinline__ float red64(float x) { x = red16(x); x += __shfl_xor(x, 16); x += __shfl_xor(x, 32); return x; }
;     ...
;                     if (nsl && r >= TP) {
;                         const float* s = scr + (size_t)(r - TP) * DM + i * 256 + lane * 4;
;                         for (int q = 0; q < nsl; ++q) v[b][i] = v[b][i] + *(const f32x4*)(s + (size_t)q * TS * DM);
;                         if (!final_inplace) *(f32x4*)(X + (size_t)r * DM + i * 256 + lane * 4) = v[b][i]; }
;                     ss += v[b][i][0] * v[b][i][0] + v[b][i][1] * v[b][i][1] + v[b][i][2] * v[b][i][2] + v[b][i][3] * v[b][i][3]; }
;                 ss = red64(ss);
;                 const float sc = rsqrtf(ss * (1.0f / DM) + EPS);
; #pragma unroll
;                 for (int i = 0; i < 4; ++i) {
;                     if (srcP && copy_x) *(f32x4*)(X + (size_t)r * DM + i * 256 + lane * 4) = v[b][i];
;                     f32x4 o = v[b][i] * sc * gv[i];
;                     if (final_inplace) *(f32x4*)(X + (size_t)r * DM + i * 256 + lane * 4) = o;
;                     else { u32x2 w; w.x = pkh(o[0], o[1]); w.y = pkh(o[2], o[3]); *(u32x2*)(XN + (size_t)r * DM + i * 256 + lane * 4) = w; }
;                 } } }
.Lpb_slow_b:
	s_waitcnt vmcnt(0)
	v_pk_add_f32 v[78:79], v[78:79], v[120:121]
	v_pk_add_f32 v[80:81], v[80:81], v[122:123]
	v_pk_add_f32 v[78:79], v[78:79], v[140:141]
	v_pk_add_f32 v[80:81], v[80:81], v[142:143]
	v_pk_add_f32 v[78:79], v[78:79], v[156:157]
	v_pk_add_f32 v[80:81], v[80:81], v[158:159]
	v_pk_add_f32 v[78:79], v[78:79], v[172:173]
	v_pk_add_f32 v[80:81], v[80:81], v[174:175]
	v_pk_add_f32 v[74:75], v[74:75], v[124:125]
	v_pk_add_f32 v[76:77], v[76:77], v[126:127]
	v_pk_add_f32 v[74:75], v[74:75], v[144:145]
	v_pk_add_f32 v[76:77], v[76:77], v[146:147]
	v_pk_add_f32 v[74:75], v[74:75], v[160:161]
	v_pk_add_f32 v[76:77], v[76:77], v[162:163]
	v_pk_add_f32 v[74:75], v[74:75], v[176:177]
	v_pk_add_f32 v[76:77], v[76:77], v[178:179]
	v_pk_add_f32 v[70:71], v[70:71], v[128:129]
	v_pk_add_f32 v[72:73], v[72:73], v[130:131]
	v_pk_add_f32 v[70:71], v[70:71], v[148:149]
	v_pk_add_f32 v[72:73], v[72:73], v[150:151]
	v_pk_add_f32 v[70:71], v[70:71], v[164:165]
	v_pk_add_f32 v[72:73], v[72:73], v[166:167]
	v_pk_add_f32 v[70:71], v[70:71], v[180:181]
	v_pk_add_f32 v[72:73], v[72:73], v[182:183]
	v_pk_add_f32 v[66:67], v[66:67], v[132:133]
	v_pk_add_f32 v[68:69], v[68:69], v[134:135]
	v_pk_add_f32 v[66:67], v[66:67], v[152:153]
	v_pk_add_f32 v[68:69], v[68:69], v[154:155]
	v_pk_add_f32 v[66:67], v[66:67], v[168:169]
	v_pk_add_f32 v[68:69], v[68:69], v[170:171]
	v_pk_add_f32 v[66:67], v[66:67], v[184:185]
	v_pk_add_f32 v[68:69], v[68:69], v[186:187]
	v_add_co_u32_e32 v192, vcc, 0x800000, v100
	s_nop 1
	v_addc_co_u32_e32 v193, vcc, 0, v101, vcc
	global_load_dwordx4 v[120:123], v[192:193], off
	global_load_dwordx4 v[124:127], v[192:193], off offset:1024
	global_load_dwordx4 v[128:131], v[192:193], off offset:2048
	global_load_dwordx4 v[132:135], v[192:193], off offset:3072
	v_add_co_u32_e32 v136, vcc, 0xa00000, v100
	s_nop 1
	v_addc_co_u32_e32 v137, vcc, 0, v101, vcc
	global_load_dwordx4 v[140:143], v[136:137], off
	global_load_dwordx4 v[144:147], v[136:137], off offset:1024
	global_load_dwordx4 v[148:151], v[136:137], off offset:2048
	global_load_dwordx4 v[152:155], v[136:137], off offset:3072
	v_add_co_u32_e32 v188, vcc, 0xc00000, v100
	s_nop 1
	v_addc_co_u32_e32 v189, vcc, 0, v101, vcc
	global_load_dwordx4 v[156:159], v[188:189], off
	global_load_dwordx4 v[160:163], v[188:189], off offset:1024
	global_load_dwordx4 v[164:167], v[188:189], off offset:2048
	global_load_dwordx4 v[168:171], v[188:189], off offset:3072
	v_add_co_u32_e32 v190, vcc, 0xe00000, v100
	s_nop 1
	v_addc_co_u32_e32 v191, vcc, 0, v101, vcc
	global_load_dwordx4 v[172:175], v[190:191], off
	global_load_dwordx4 v[176:179], v[190:191], off offset:1024
	global_load_dwordx4 v[180:183], v[190:191], off offset:2048
	global_load_dwordx4 v[184:187], v[190:191], off offset:3072
	s_waitcnt vmcnt(0)
	v_pk_add_f32 v[78:79], v[78:79], v[120:121]
	v_pk_add_f32 v[80:81], v[80:81], v[122:123]
	v_pk_add_f32 v[78:79], v[78:79], v[140:141]
	v_pk_add_f32 v[80:81], v[80:81], v[142:143]
	v_pk_add_f32 v[78:79], v[78:79], v[156:157]
	v_pk_add_f32 v[80:81], v[80:81], v[158:159]
	v_pk_add_f32 v[78:79], v[78:79], v[172:173]
	v_pk_add_f32 v[80:81], v[80:81], v[174:175]
	v_pk_add_f32 v[74:75], v[74:75], v[124:125]
	v_pk_add_f32 v[76:77], v[76:77], v[126:127]
	v_pk_add_f32 v[74:75], v[74:75], v[144:145]
	v_pk_add_f32 v[76:77], v[76:77], v[146:147]
	v_pk_add_f32 v[74:75], v[74:75], v[160:161]
	v_pk_add_f32 v[76:77], v[76:77], v[162:163]
	v_pk_add_f32 v[74:75], v[74:75], v[176:177]
	v_pk_add_f32 v[76:77], v[76:77], v[178:179]
	v_pk_add_f32 v[70:71], v[70:71], v[128:129]
	v_pk_add_f32 v[72:73], v[72:73], v[130:131]
	v_pk_add_f32 v[70:71], v[70:71], v[148:149]
	v_pk_add_f32 v[72:73], v[72:73], v[150:151]
	v_pk_add_f32 v[70:71], v[70:71], v[164:165]
	v_pk_add_f32 v[72:73], v[72:73], v[166:167]
	v_pk_add_f32 v[70:71], v[70:71], v[180:181]
	v_pk_add_f32 v[72:73], v[72:73], v[182:183]
	v_pk_add_f32 v[66:67], v[66:67], v[132:133]
	v_pk_add_f32 v[68:69], v[68:69], v[134:135]
	v_pk_add_f32 v[66:67], v[66:67], v[152:153]
	v_pk_add_f32 v[68:69], v[68:69], v[154:155]
	v_pk_add_f32 v[66:67], v[66:67], v[168:169]
	v_pk_add_f32 v[68:69], v[68:69], v[170:171]
	v_pk_add_f32 v[66:67], v[66:67], v[184:185]
	v_pk_add_f32 v[68:69], v[68:69], v[186:187]
.Lpb_store_b:
.LBB0_711:
	s_or_b64 exec, exec, s[4:5]
	s_waitcnt vmcnt(3)
	v_mul_f32_e32 v16, v79, v79
	s_waitcnt vmcnt(2)
	v_mul_f32_e32 v100, v75, v75
	v_fmac_f32_e32 v16, v78, v78
	v_fmac_f32_e32 v100, v74, v74
	v_fmac_f32_e32 v16, v80, v80
	v_fmac_f32_e32 v100, v76, v76
	v_fmac_f32_e32 v16, v81, v81
	v_fmac_f32_e32 v100, v77, v77
	v_add_f32_e32 v16, v16, v100
	s_waitcnt vmcnt(1)
	v_mul_f32_e32 v100, v71, v71
	v_fmac_f32_e32 v100, v70, v70
	v_fmac_f32_e32 v100, v72, v72
	v_fmac_f32_e32 v100, v73, v73
	s_waitcnt vmcnt(0)
	v_pk_mul_f32 v[106:107], v[66:67], v[66:67]
	v_add_f32_e32 v16, v16, v100
	v_pk_mul_f32 v[100:101], v[68:69], v[68:69]
	v_add_f32_e32 v106, v106, v107
	v_add_f32_e32 v100, v100, v106
	v_add_f32_e32 v100, v101, v100
	v_add_f32_e32 v16, v16, v100
	s_nop 1
	v_add_f32_dpp v16, v16, v16 quad_perm:[1,0,3,2] row_mask:0xf bank_mask:0xf bound_ctrl:1
	s_nop 1
	v_add_f32_dpp v16, v16, v16 quad_perm:[2,3,0,1] row_mask:0xf bank_mask:0xf bound_ctrl:1
	s_nop 1
	v_add_f32_dpp v16, v16, v16 row_half_mirror row_mask:0xf bank_mask:0xf bound_ctrl:1
	s_nop 1
	v_add_f32_dpp v16, v16, v16 row_mirror row_mask:0xf bank_mask:0xf bound_ctrl:1
	ds_bpermute_b32 v100, v103, v16
	s_waitcnt lgkmcnt(0)
	v_add_f32_e32 v16, v16, v100
	ds_bpermute_b32 v100, v104, v16
	s_waitcnt lgkmcnt(0)
	v_add_f32_e32 v16, v16, v100
	v_fmamk_f32 v16, v16, 0x3a800000, v203
	v_mul_f32_e32 v100, 0x4b800000, v16
	v_cmp_gt_f32_e32 vcc, s16, v16
	s_nop 1
	v_cndmask_b32_e32 v16, v16, v100, vcc
	v_rsq_f32_e32 v16, v16
	s_nop 0
	v_mul_f32_e32 v100, 0x45800000, v16
	v_cndmask_b32_e32 v16, v16, v100, vcc
	v_pk_mul_f32 v[78:79], v[78:79], v[16:17] op_sel_hi:[1,0]
	v_pk_mul_f32 v[80:81], v[80:81], v[16:17] op_sel_hi:[1,0]
	v_pk_mul_f32 v[74:75], v[74:75], v[16:17] op_sel_hi:[1,0]
	v_pk_mul_f32 v[76:77], v[76:77], v[16:17] op_sel_hi:[1,0]
	v_pk_mul_f32 v[70:71], v[70:71], v[16:17] op_sel_hi:[1,0]
	v_pk_mul_f32 v[72:73], v[72:73], v[16:17] op_sel_hi:[1,0]
	v_pk_mul_f32 v[66:67], v[66:67], v[16:17] op_sel_hi:[1,0]
	v_pk_mul_f32 v[68:69], v[68:69], v[16:17] op_sel_hi:[1,0]
	v_pk_mul_f32 v[80:81], v[2:3], v[80:81]
	v_pk_mul_f32 v[78:79], v[0:1], v[78:79]
	v_pk_mul_f32 v[76:77], v[6:7], v[76:77]
	v_pk_mul_f32 v[74:75], v[4:5], v[74:75]
	v_pk_mul_f32 v[72:73], v[10:11], v[72:73]
	v_pk_mul_f32 v[70:71], v[8:9], v[70:71]
	v_pk_mul_f32 v[68:69], v[14:15], v[68:69]
	v_pk_mul_f32 v[66:67], v[12:13], v[66:67]
	global_store_dwordx4 v[98:99], v[78:81], off
	global_store_dwordx4 v[98:99], v[74:77], off offset:1024
	global_store_dwordx4 v[98:99], v[70:73], off offset:2048
	global_store_dwordx4 v[98:99], v[66:69], off offset:3072
	s_and_saveexec_b64 s[4:5], s[44:45]
	s_cbranch_execnz .LBB0_717
	s_or_b64 exec, exec, s[4:5]
	s_and_saveexec_b64 s[4:5], s[42:43]
	s_cbranch_execnz .LBB0_723

;     ...
;         for (int b = 0; b < 4; ++b) { const int r = r0 + b * nw;
;             if (r < TT) {
;                 float ss = 0.f;
; #pragma unroll
;                 for (int i = 0; i < 4; ++i) {
;                     if (nsl && r >= TP) {
;                         const float* s = scr + (size_t)(r - TP) * DM + i * 256 + lane * 4;
;                         for (int q = 0; q < nsl; ++q) v[b][i] = v[b][i] + *(const f32x4*)(s + (size_t)q * TS * DM);
;                         if (!final_inplace) *(f32x4*)(X + (size_t)r * DM + i * 256 + lane * 4) = v[b][i]; }
;                     ss += v[b][i][0] * v[b][i][0] + v[b][i][1] * v[b][i][1] + v[b][i][2] * v[b][i][2] + v[b][i][3] * v[b][i][3]; }
.LBB0_755:
	s_or_b64 exec, exec, s[4:5]
	v_add_u32_e32 v16, 0xffffc000, v82
	v_lshlrev_b64 v[108:109], 12, v[16:17]
	v_mov_b32_e32 v83, v17
	v_lshl_add_u64 v[110:111], v[84:85], 0, v[108:109]
	v_lshlrev_b64 v[108:109], 12, v[82:83]
	v_cmp_lt_i32_e64 s[46:47], s15, v82
	v_lshl_add_u64 v[108:109], v[86:87], 0, v[108:109]
	s_and_saveexec_b64 s[4:5], s[46:47]
	s_cbranch_execz .LBB0_760
	global_load_dwordx4 v[120:123], v[110:111], off
	global_load_dwordx4 v[124:127], v[110:111], off offset:1024
	global_load_dwordx4 v[128:131], v[110:111], off offset:2048
	global_load_dwordx4 v[132:135], v[110:111], off offset:3072
	v_add_co_u32_e32 v136, vcc, 0x200000, v110
	s_nop 1
	v_addc_co_u32_e32 v137, vcc, 0, v111, vcc
	global_load_dwordx4 v[140:143], v[136:137], off
	global_load_dwordx4 v[144:147], v[136:137], off offset:1024
	global_load_dwordx4 v[148:151], v[136:137], off offset:2048
	global_load_dwordx4 v[152:155], v[136:137], off offset:3072
	v_add_co_u32_e32 v188, vcc, 0x400000, v110
	s_nop 1
	v_addc_co_u32_e32 v189, vcc, 0, v111, vcc
	global_load_dwordx4 v[156:159], v[188:189], off
	global_load_dwordx4 v[160:163], v[188:189], off offset:1024
	global_load_dwordx4 v[164:167], v[188:189], off offset:2048
	global_load_dwordx4 v[168:171], v[188:189], off offset:3072
	v_add_co_u32_e32 v190, vcc, 0x600000, v110
	s_nop 1
	v_addc_co_u32_e32 v191, vcc, 0, v111, vcc
	global_load_dwordx4 v[172:175], v[190:191], off
	global_load_dwordx4 v[176:179], v[190:191], off offset:1024
	global_load_dwordx4 v[180:183], v[190:191], off offset:2048
	global_load_dwordx4 v[184:187], v[190:191], off offset:3072
	s_or_b64 s[6:7], s[44:45], s[42:43]
	s_or_b64 s[6:7], s[6:7], s[40:41]
	s_cmp_eq_u64 s[6:7], 0
	s_cbranch_scc0 .Lpb_slow_a
	v_add_co_u32_e32 v192, vcc, 0x800000, v110
	s_nop 1
	v_addc_co_u32_e32 v193, vcc, 0, v111, vcc
	global_load_dwordx4 v[18:21], v[192:193], off
	global_load_dwordx4 v[22:25], v[192:193], off offset:1024
	global_load_dwordx4 v[26:29], v[192:193], off offset:2048
	global_load_dwordx4 v[30:33], v[192:193], off offset:3072
	v_add_co_u32_e32 v136, vcc, 0xa00000, v110
	s_nop 1
	v_addc_co_u32_e32 v137, vcc, 0, v111, vcc
	global_load_dwordx4 v[34:37], v[136:137], off
	global_load_dwordx4 v[38:41], v[136:137], off offset:1024
	global_load_dwordx4 v[42:45], v[136:137], off offset:2048
	global_load_dwordx4 v[46:49], v[136:137], off offset:3072
	v_add_co_u32_e32 v188, vcc, 0xc00000, v110
	s_nop 1
	v_addc_co_u32_e32 v189, vcc, 0, v111, vcc
	global_load_dwordx4 v[50:53], v[188:189], off
	global_load_dwordx4 v[54:57], v[188:189], off offset:1024
	global_load_dwordx4 v[58:61], v[188:189], off offset:2048
	global_load_dwordx4 v[62:65], v[188:189], off offset:3072
	v_add_co_u32_e32 v190, vcc, 0xe00000, v110
	s_nop 1
	v_addc_co_u32_e32 v191, vcc, 0, v111, vcc
	global_load_dwordx4 v[230:233], v[190:191], off
	global_load_dwordx4 v[234:237], v[190:191], off offset:1024
	global_load_dwordx4 v[238:241], v[190:191], off offset:2048
	global_load_dwordx4 v[242:245], v[190:191], off offset:3072
	s_waitcnt vmcnt(0)
	v_pk_add_f32 v[78:79], v[78:79], v[120:121]
	v_pk_add_f32 v[80:81], v[80:81], v[122:123]
	v_pk_add_f32 v[78:79], v[78:79], v[140:141]
	v_pk_add_f32 v[80:81], v[80:81], v[142:143]
	v_pk_add_f32 v[78:79], v[78:79], v[156:157]
	v_pk_add_f32 v[80:81], v[80:81], v[158:159]
	v_pk_add_f32 v[78:79], v[78:79], v[172:173]
	v_pk_add_f32 v[80:81], v[80:81], v[174:175]
	v_pk_add_f32 v[74:75], v[74:75], v[124:125]
	v_pk_add_f32 v[76:77], v[76:77], v[126:127]
	v_pk_add_f32 v[74:75], v[74:75], v[144:145]
	v_pk_add_f32 v[76:77], v[76:77], v[146:147]
	v_pk_add_f32 v[74:75], v[74:75], v[160:161]
	v_pk_add_f32 v[76:77], v[76:77], v[162:163]
	v_pk_add_f32 v[74:75], v[74:75], v[176:177]
	v_pk_add_f32 v[76:77], v[76:77], v[178:179]
	v_pk_add_f32 v[70:71], v[70:71], v[128:129]
	v_pk_add_f32 v[72:73], v[72:73], v[130:131]
	v_pk_add_f32 v[70:71], v[70:71], v[148:149]
	v_pk_add_f32 v[72:73], v[72:73], v[150:151]
	v_pk_add_f32 v[70:71], v[70:71], v[164:165]
	v_pk_add_f32 v[72:73], v[72:73], v[166:167]
	v_pk_add_f32 v[70:71], v[70:71], v[180:181]
	v_pk_add_f32 v[72:73], v[72:73], v[182:183]
	v_pk_add_f32 v[66:67], v[66:67], v[132:133]
	v_pk_add_f32 v[68:69], v[68:69], v[134:135]
	v_pk_add_f32 v[66:67], v[66:67], v[152:153]
	v_pk_add_f32 v[68:69], v[68:69], v[154:155]
	v_pk_add_f32 v[66:67], v[66:67], v[168:169]
	v_pk_add_f32 v[68:69], v[68:69], v[170:171]
	v_pk_add_f32 v[66:67], v[66:67], v[184:185]
	v_pk_add_f32 v[68:69], v[68:69], v[186:187]
	v_pk_add_f32 v[78:79], v[78:79], v[18:19]
	v_pk_add_f32 v[80:81], v[80:81], v[20:21]
	v_pk_add_f32 v[78:79], v[78:79], v[34:35]
	v_pk_add_f32 v[80:81], v[80:81], v[36:37]
	v_pk_add_f32 v[78:79], v[78:79], v[50:51]
	v_pk_add_f32 v[80:81], v[80:81], v[52:53]
	v_pk_add_f32 v[78:79], v[78:79], v[230:231]
	v_pk_add_f32 v[80:81], v[80:81], v[232:233]
	v_pk_add_f32 v[74:75], v[74:75], v[22:23]
	v_pk_add_f32 v[76:77], v[76:77], v[24:25]
	v_pk_add_f32 v[74:75], v[74:75], v[38:39]
	v_pk_add_f32 v[76:77], v[76:77], v[40:41]
	v_pk_add_f32 v[74:75], v[74:75], v[54:55]
	v_pk_add_f32 v[76:77], v[76:77], v[56:57]
	v_pk_add_f32 v[74:75], v[74:75], v[234:235]
	v_pk_add_f32 v[76:77], v[76:77], v[236:237]
	v_pk_add_f32 v[70:71], v[70:71], v[26:27]
	v_pk_add_f32 v[72:73], v[72:73], v[28:29]
	v_pk_add_f32 v[70:71], v[70:71], v[42:43]
	v_pk_add_f32 v[72:73], v[72:73], v[44:45]
	v_pk_add_f32 v[70:71], v[70:71], v[58:59]
	v_pk_add_f32 v[72:73], v[72:73], v[60:61]
	v_pk_add_f32 v[70:71], v[70:71], v[238:239]
	v_pk_add_f32 v[72:73], v[72:73], v[240:241]
	v_pk_add_f32 v[66:67], v[66:67], v[30:31]
	v_pk_add_f32 v[68:69], v[68:69], v[32:33]
	v_pk_add_f32 v[66:67], v[66:67], v[46:47]
	v_pk_add_f32 v[68:69], v[68:69], v[48:49]
	v_pk_add_f32 v[66:67], v[66:67], v[62:63]
	v_pk_add_f32 v[68:69], v[68:69], v[64:65]
	v_pk_add_f32 v[66:67], v[66:67], v[242:243]
	v_pk_add_f32 v[68:69], v[68:69], v[244:245]
	s_branch .Lpb_store_a
;     ...
;                     if (nsl && r >= TP) {
;                         const float* s = scr + (size_t)(r - TP) * DM + i * 256 + lane * 4;
;                         for (int q = 0; q < nsl; ++q) v[b][i] = v[b][i] + *(const f32x4*)(s + (size_t)q * TS * DM);
;                         if (!final_inplace) *(f32x4*)(X + (size_t)r * DM + i * 256 + lane * 4) = v[b][i]; }
.Lpb_slow_a:
	s_waitcnt vmcnt(0)
	v_pk_add_f32 v[78:79], v[78:79], v[120:121]
	v_pk_add_f32 v[80:81], v[80:81], v[122:123]
	v_pk_add_f32 v[78:79], v[78:79], v[140:141]
	v_pk_add_f32 v[80:81], v[80:81], v[142:143]
	v_pk_add_f32 v[78:79], v[78:79], v[156:157]
	v_pk_add_f32 v[80:81], v[80:81], v[158:159]
	v_pk_add_f32 v[78:79], v[78:79], v[172:173]
	v_pk_add_f32 v[80:81], v[80:81], v[174:175]
	v_pk_add_f32 v[74:75], v[74:75], v[124:125]
	v_pk_add_f32 v[76:77], v[76:77], v[126:127]
	v_pk_add_f32 v[74:75], v[74:75], v[144:145]
	v_pk_add_f32 v[76:77], v[76:77], v[146:147]
	v_pk_add_f32 v[74:75], v[74:75], v[160:161]
	v_pk_add_f32 v[76:77], v[76:77], v[162:163]
	v_pk_add_f32 v[74:75], v[74:75], v[176:177]
	v_pk_add_f32 v[76:77], v[76:77], v[178:179]
	v_pk_add_f32 v[70:71], v[70:71], v[128:129]
	v_pk_add_f32 v[72:73], v[72:73], v[130:131]
	v_pk_add_f32 v[70:71], v[70:71], v[148:149]
	v_pk_add_f32 v[72:73], v[72:73], v[150:151]
	v_pk_add_f32 v[70:71], v[70:71], v[164:165]
	v_pk_add_f32 v[72:73], v[72:73], v[166:167]
	v_pk_add_f32 v[70:71], v[70:71], v[180:181]
	v_pk_add_f32 v[72:73], v[72:73], v[182:183]
	v_pk_add_f32 v[66:67], v[66:67], v[132:133]
	v_pk_add_f32 v[68:69], v[68:69], v[134:135]
	v_pk_add_f32 v[66:67], v[66:67], v[152:153]
	v_pk_add_f32 v[68:69], v[68:69], v[154:155]
	v_pk_add_f32 v[66:67], v[66:67], v[168:169]
	v_pk_add_f32 v[68:69], v[68:69], v[170:171]
	v_pk_add_f32 v[66:67], v[66:67], v[184:185]
	v_pk_add_f32 v[68:69], v[68:69], v[186:187]
	v_add_co_u32_e32 v192, vcc, 0x800000, v110
	s_nop 1
	v_addc_co_u32_e32 v193, vcc, 0, v111, vcc
	global_load_dwordx4 v[120:123], v[192:193], off
	global_load_dwordx4 v[124:127], v[192:193], off offset:1024
	global_load_dwordx4 v[128:131], v[192:193], off offset:2048
	global_load_dwordx4 v[132:135], v[192:193], off offset:3072
	v_add_co_u32_e32 v136, vcc, 0xa00000, v110
	s_nop 1
	v_addc_co_u32_e32 v137, vcc, 0, v111, vcc
	global_load_dwordx4 v[140:143], v[136:137], off
	global_load_dwordx4 v[144:147], v[136:137], off offset:1024
	global_load_dwordx4 v[148:151], v[136:137], off offset:2048
	global_load_dwordx4 v[152:155], v[136:137], off offset:3072
	v_add_co_u32_e32 v188, vcc, 0xc00000, v110
	s_nop 1
	v_addc_co_u32_e32 v189, vcc, 0, v111, vcc
	global_load_dwordx4 v[156:159], v[188:189], off
	global_load_dwordx4 v[160:163], v[188:189], off offset:1024
	global_load_dwordx4 v[164:167], v[188:189], off offset:2048
	global_load_dwordx4 v[168:171], v[188:189], off offset:3072
	v_add_co_u32_e32 v190, vcc, 0xe00000, v110
	s_nop 1
	v_addc_co_u32_e32 v191, vcc, 0, v111, vcc
	global_load_dwordx4 v[172:175], v[190:191], off
	global_load_dwordx4 v[176:179], v[190:191], off offset:1024
	global_load_dwordx4 v[180:183], v[190:191], off offset:2048
	global_load_dwordx4 v[184:187], v[190:191], off offset:3072
	s_waitcnt vmcnt(0)
	v_pk_add_f32 v[78:79], v[78:79], v[120:121]
	v_pk_add_f32 v[80:81], v[80:81], v[122:123]
	v_pk_add_f32 v[78:79], v[78:79], v[140:141]
	v_pk_add_f32 v[80:81], v[80:81], v[142:143]
	v_pk_add_f32 v[78:79], v[78:79], v[156:157]
	v_pk_add_f32 v[80:81], v[80:81], v[158:159]
	v_pk_add_f32 v[78:79], v[78:79], v[172:173]
	v_pk_add_f32 v[80:81], v[80:81], v[174:175]
	v_pk_add_f32 v[74:75], v[74:75], v[124:125]
	v_pk_add_f32 v[76:77], v[76:77], v[126:127]
	v_pk_add_f32 v[74:75], v[74:75], v[144:145]
	v_pk_add_f32 v[76:77], v[76:77], v[146:147]
	v_pk_add_f32 v[74:75], v[74:75], v[160:161]
	v_pk_add_f32 v[76:77], v[76:77], v[162:163]
	v_pk_add_f32 v[74:75], v[74:75], v[176:177]
	v_pk_add_f32 v[76:77], v[76:77], v[178:179]
	v_pk_add_f32 v[70:71], v[70:71], v[128:129]
	v_pk_add_f32 v[72:73], v[72:73], v[130:131]
	v_pk_add_f32 v[70:71], v[70:71], v[148:149]
	v_pk_add_f32 v[72:73], v[72:73], v[150:151]
	v_pk_add_f32 v[70:71], v[70:71], v[164:165]
	v_pk_add_f32 v[72:73], v[72:73], v[166:167]
	v_pk_add_f32 v[70:71], v[70:71], v[180:181]
	v_pk_add_f32 v[72:73], v[72:73], v[182:183]
	v_pk_add_f32 v[66:67], v[66:67], v[132:133]
	v_pk_add_f32 v[68:69], v[68:69], v[134:135]
	v_pk_add_f32 v[66:67], v[66:67], v[152:153]
	v_pk_add_f32 v[68:69], v[68:69], v[154:155]
	v_pk_add_f32 v[66:67], v[66:67], v[168:169]
	v_pk_add_f32 v[68:69], v[68:69], v[170:171]
	v_pk_add_f32 v[66:67], v[66:67], v[184:185]
	v_pk_add_f32 v[68:69], v[68:69], v[186:187]
.Lpb_store_a:
	global_store_dwordx4 v[108:109], v[78:81], off
	global_store_dwordx4 v[108:109], v[74:77], off offset:1024
	global_store_dwordx4 v[108:109], v[70:73], off offset:2048
	global_store_dwordx4 v[108:109], v[66:69], off offset:3072
